# entry grid sync removed; scan workgroups skip the phase-4 GEMM queue (only when the grid is 256 workgroups)
# baseline (speedup 1.0000x reference)
; #define LAS __attribute__((address_space(3)))
; __global__ void __launch_bounds__(NWAVES * 64, 2) hybrid_fwd(Args A) {
;     ...
;         if (G >= 256) { if ((vcu & 31) < 12 && vcu < 256) sidx = (vcu >> 5) * 12 + (vcu & 31); }
;         if (!(A.flags & 1)) {
;             if (sidx >= 0) scan_unit(A, lds, sidx, tid);
;             else if (G < 256) { for (int s = bx; s < 96; s += G) scan_unit(A, lds, s, tid); }
;         }
;         if (!(A.flags & 2)) {
;             __syncthreads();
;             pg8::Gemm g{H, WinT + (size_t)5888 * DMODEL, M, 8960, DMODEL}; pg8::QueueSched S{ctl + 128, (volatile LAS unsigned*)(MISC + 16), 32 * 35, 35, wave0};
.LBB0_511:
	s_load_dword s0, s[62:63], 0xb8
	s_waitcnt lgkmcnt(0)
	s_cmpk_lg_u32 s0, 0x100
	s_cbranch_scc1 .Lnq_no
	s_cmp_lt_u32 s97, 96
	s_cbranch_scc1 .LBB0_579
